# baseline (speedup 1.0000x reference)
.LBB0_671:
	v_lshl_add_u64 v[2:3], s[2:3], 1, v[140:141]
	v_lshl_add_u64 v[60:61], v[2:3], 0, v[136:137]
	v_add_co_u32_e32 v60, vcc, 0x1000, v60
	s_nop 1
	v_addc_co_u32_e32 v61, vcc, 0, v61, vcc
	global_load_dwordx2 v[4:5], v[146:147], off
	global_load_dwordx2 v[6:7], v[146:147], off offset:32
	global_load_dwordx2 v[8:9], v[146:147], off offset:64
	global_load_dwordx2 v[10:11], v[146:147], off offset:96
	global_load_dwordx2 v[12:13], v[148:149], off
	global_load_dwordx2 v[14:15], v[148:149], off offset:32
	global_load_dwordx2 v[16:17], v[148:149], off offset:64
	global_load_dwordx2 v[18:19], v[148:149], off offset:96
	global_load_ushort v0, v[60:61], off offset:1022
	v_cndmask_b32_e64 v60, 0, 1, s[66:67]
	v_cmp_ne_u32_e64 s[54:55], 1, v60
	s_waitcnt vmcnt(0)
	v_lshlrev_b32_e32 v0, 16, v0
	v_mul_f32_e32 v0, 0xbfb8aa3b, v0
	v_exp_f32_e32 v0, v0
	s_nop 0
	v_add_f32_e32 v0, 1.0, v0
	v_div_scale_f32 v61, s[6:7], v0, v0, 1.0
	v_rcp_f32_e32 v62, v61
	v_div_scale_f32 v60, vcc, 1.0, v0, 1.0
	v_fma_f32 v63, -v61, v62, 1.0
	v_fmac_f32_e32 v62, v63, v62
	v_mul_f32_e32 v63, v60, v62
	v_fma_f32 v64, -v61, v63, v60
	v_fmac_f32_e32 v63, v64, v62
	v_fma_f32 v60, -v61, v63, v60
	v_div_fmas_f32 v60, v60, v62, v63
	s_andn2_b64 vcc, exec, s[66:67]
	v_div_fixup_f32 v60, v60, v0, 1.0
	s_cbranch_vccnz .LBB0_673
	v_mov_b32_e32 v0, v246
	v_mov_b32_e32 v61, v246
	s_nop 1
	v_permlane16_swap_b32_e32 v0, v61
	v_add_f32_e32 v0, v0, v61
	v_mov_b32_e32 v61, v0
	s_nop 1
	v_permlane32_swap_b32_e32 v0, v61
	v_add_f32_e32 v0, v0, v61
	v_div_scale_f32 v61, s[6:7], v0, v0, v60
	v_rcp_f32_e32 v62, v61
	s_nop 0
	v_fma_f32 v63, -v61, v62, 1.0
	v_fmac_f32_e32 v62, v63, v62
	v_div_scale_f32 v63, vcc, v60, v0, v60
	v_mul_f32_e32 v64, v63, v62
	v_fma_f32 v65, -v61, v64, v63
	v_fmac_f32_e32 v64, v65, v62
	v_fma_f32 v61, -v61, v64, v63
	v_div_fmas_f32 v61, v61, v62, v64
	v_div_fixup_f32 v60, v61, v0, v60
.LBB0_673:
	v_mov_b32_e32 v62, 0
	s_and_b64 vcc, exec, s[54:55]
	v_mov_b32_e32 v66, 0
	v_mov_b32_e32 v67, 0
	v_mov_b32_e32 v64, 0
	v_mov_b32_e32 v65, 0
	s_cbranch_vccnz .LBB0_675
	v_mov_b32_e32 v64, v4
	v_mov_b32_e32 v65, v5
	v_lshlrev_b32_e32 v66, 16, v64
	v_and_b32_e32 v67, 0xffff0000, v64
	v_lshlrev_b32_e32 v64, 16, v65
	v_and_b32_e32 v65, 0xffff0000, v65
.LBB0_675:
	v_pk_fma_f32 v[66:67], v[88:89], v[60:61], v[66:67] op_sel_hi:[1,0,1]
	v_pk_fma_f32 v[64:65], v[90:91], v[60:61], v[64:65] op_sel_hi:[1,0,1]
	v_cvt_pk_bf16_f32 v66, v66, v67
	v_cvt_pk_bf16_f32 v67, v64, v65
	s_and_b64 vcc, exec, s[54:55]
	v_mov_b32_e32 v63, 0
	v_mov_b32_e32 v64, 0
	v_mov_b32_e32 v65, 0
	global_store_dwordx2 v[146:147], v[66:67], off
	s_cbranch_vccnz .LBB0_677
	v_mov_b32_e32 v64, v6
	v_mov_b32_e32 v65, v7
	v_lshlrev_b32_e32 v62, 16, v64
	v_and_b32_e32 v63, 0xffff0000, v64
	v_lshlrev_b32_e32 v64, 16, v65
	v_and_b32_e32 v65, 0xffff0000, v65
.LBB0_677:
	v_mov_b32_e32 v61, v60
	v_pk_fma_f32 v[62:63], v[84:85], v[60:61], v[62:63]
	v_pk_fma_f32 v[64:65], v[86:87], v[60:61], v[64:65]
	v_cvt_pk_bf16_f32 v62, v62, v63
	v_cvt_pk_bf16_f32 v63, v64, v65
	global_store_dwordx2 v[146:147], v[62:63], off offset:32
	v_mov_b32_e32 v62, 0
	s_and_b64 vcc, exec, s[54:55]
	v_mov_b32_e32 v66, 0
	v_mov_b32_e32 v67, 0
	v_mov_b32_e32 v64, 0
	v_mov_b32_e32 v65, 0
	s_cbranch_vccnz .LBB0_679
	v_mov_b32_e32 v64, v8
	v_mov_b32_e32 v65, v9
	v_lshlrev_b32_e32 v66, 16, v64
	v_and_b32_e32 v67, 0xffff0000, v64
	v_lshlrev_b32_e32 v64, 16, v65
	v_and_b32_e32 v65, 0xffff0000, v65
.LBB0_679:
	v_pk_fma_f32 v[66:67], v[80:81], v[60:61], v[66:67]
	v_pk_fma_f32 v[64:65], v[82:83], v[60:61], v[64:65]
	v_cvt_pk_bf16_f32 v66, v66, v67
	v_cvt_pk_bf16_f32 v67, v64, v65
	s_and_b64 vcc, exec, s[54:55]
	v_mov_b32_e32 v63, 0
	v_mov_b32_e32 v64, 0
	v_mov_b32_e32 v65, 0
	global_store_dwordx2 v[146:147], v[66:67], off offset:64
	s_cbranch_vccnz .LBB0_681
	v_mov_b32_e32 v64, v10
	v_mov_b32_e32 v65, v11
	v_lshlrev_b32_e32 v62, 16, v64
	v_and_b32_e32 v63, 0xffff0000, v64
	v_lshlrev_b32_e32 v64, 16, v65
	v_and_b32_e32 v65, 0xffff0000, v65

.LBB0_683:
	v_mov_b32_e32 v60, 0
	s_and_b64 vcc, exec, s[54:55]
	v_mov_b32_e32 v64, 0
	v_mov_b32_e32 v65, 0
	v_mov_b32_e32 v62, 0
	v_mov_b32_e32 v63, 0
	s_cbranch_vccnz .LBB0_685
	v_mov_b32_e32 v62, v12
	v_mov_b32_e32 v63, v13
	v_lshlrev_b32_e32 v64, 16, v62
	v_and_b32_e32 v65, 0xffff0000, v62
	v_lshlrev_b32_e32 v62, 16, v63
	v_and_b32_e32 v63, 0xffff0000, v63
.LBB0_685:
	v_pk_fma_f32 v[56:57], v[56:57], v[2:3], v[64:65] op_sel_hi:[1,0,1]
	v_pk_fma_f32 v[58:59], v[58:59], v[2:3], v[62:63] op_sel_hi:[1,0,1]
	v_cvt_pk_bf16_f32 v56, v56, v57
	v_cvt_pk_bf16_f32 v57, v58, v59
	global_store_dwordx2 v[148:149], v[56:57], off
	s_and_b64 vcc, exec, s[54:55]
	v_mov_b32_e32 v61, 0
	v_mov_b32_e32 v56, 0
	v_mov_b32_e32 v57, 0
	s_cbranch_vccnz .LBB0_687
	v_mov_b32_e32 v56, v14
	v_mov_b32_e32 v57, v15
	v_lshlrev_b32_e32 v60, 16, v56
	v_and_b32_e32 v61, 0xffff0000, v56
	v_lshlrev_b32_e32 v56, 16, v57
	v_and_b32_e32 v57, 0xffff0000, v57
.LBB0_687:
	v_mov_b32_e32 v3, v2
	v_pk_fma_f32 v[52:53], v[52:53], v[2:3], v[60:61]
	v_pk_fma_f32 v[54:55], v[54:55], v[2:3], v[56:57]
	v_cvt_pk_bf16_f32 v52, v52, v53
	v_cvt_pk_bf16_f32 v53, v54, v55
	global_store_dwordx2 v[148:149], v[52:53], off offset:32
	v_mov_b32_e32 v52, 0
	s_and_b64 vcc, exec, s[54:55]
	v_mov_b32_e32 v56, 0
	v_mov_b32_e32 v57, 0
	v_mov_b32_e32 v54, 0
	v_mov_b32_e32 v55, 0
	s_cbranch_vccnz .LBB0_689
	v_mov_b32_e32 v54, v16
	v_mov_b32_e32 v55, v17
	v_lshlrev_b32_e32 v56, 16, v54
	v_and_b32_e32 v57, 0xffff0000, v54
	v_lshlrev_b32_e32 v54, 16, v55
	v_and_b32_e32 v55, 0xffff0000, v55
.LBB0_689:
	v_pk_fma_f32 v[48:49], v[48:49], v[2:3], v[56:57]
	v_pk_fma_f32 v[50:51], v[50:51], v[2:3], v[54:55]
	v_cvt_pk_bf16_f32 v48, v48, v49
	v_cvt_pk_bf16_f32 v49, v50, v51
	global_store_dwordx2 v[148:149], v[48:49], off offset:64
	s_and_b64 vcc, exec, s[54:55]
	v_mov_b32_e32 v53, 0
	v_mov_b32_e32 v48, 0
	v_mov_b32_e32 v49, 0
	s_cbranch_vccnz .LBB0_691
	v_mov_b32_e32 v48, v18
	v_mov_b32_e32 v49, v19
	v_lshlrev_b32_e32 v52, 16, v48
	v_and_b32_e32 v53, 0xffff0000, v48
	v_lshlrev_b32_e32 v48, 16, v49
	v_and_b32_e32 v49, 0xffff0000, v49
